# natten tile staging: one LDS store address + immediates, saddr-form global loads with 32-bit lane offsets (45 -> 12 VALU per tile, no slow mul/mad)
# speedup vs baseline: 1.0108x; 1.0108x over previous
.LBB0_442:
	s_add_i32 s3, s85, 1
	s_cmp_ge_i32 s3, s2
	s_cselect_b64 s[86:87], -1, 0
	s_and_b64 vcc, exec, s[86:87]
	s_cbranch_vccnz .LBB0_447
	s_bitcmp1_b32 s3, 0
	s_cselect_b32 s88, 0x5800, 0
	v_lshrrev_b32_e32 v168, 3, v193
	v_and_b32_e32 v169, 7, v193
	v_mul_u32_u24_e32 v168, 0x90, v168
	v_lshl_add_u32 v168, v169, 4, v168
	v_add_u32_e32 v168, s88, v168
	s_waitcnt vmcnt(3)
	ds_write_b128 v168, v[146:149]
	s_waitcnt vmcnt(2)
	ds_write_b128 v168, v[150:153] offset:4608
	s_waitcnt vmcnt(1)
	ds_write_b128 v168, v[154:157] offset:13312
	s_add_i32 s85, s85, 2
	s_cmp_ge_i32 s85, s2
	s_waitcnt vmcnt(0)
	ds_write_b128 v168, v[158:161] offset:17920
	s_cbranch_scc1 .LBB0_447
	s_cmp_gt_i32 s85, s97
	s_mov_b32 vcc_lo, s84
	s_cbranch_scc1 .Lnat_stage_ld
	s_add_i32 s85, s85, s96
	s_lshl_b32 vcc_lo, s85, 6
.Lnat_stage_ld:
	s_ashr_i32 vcc_hi, vcc_lo, 31
	s_lshl_b64 s[88:89], vcc, 7
	s_add_u32 s88, s92, s88
	s_addc_u32 s89, s93, s89
	s_lshl_b64 vcc, vcc, 1
	v_lshlrev_b32_e32 v170, 4, v193
	s_add_u32 vcc_lo, s94, vcc_lo
	s_addc_u32 vcc_hi, s95, vcc_hi
	v_add_u32_e32 v171, 0x1000, v170
	v_lshrrev_b32_e32 v172, 3, v193
	v_and_b32_e32 v173, 0x70, v170
	v_mul_u32_u24_e32 v172, 0x1200, v172
	global_load_dwordx4 v[146:149], v170, s[88:89]
	global_load_dwordx4 v[150:153], v171, s[88:89]
	v_or_b32_e32 v172, v172, v173
	v_add_u32_e32 v173, 0x24000, v172
	s_nop 0
	global_load_dwordx4 v[154:157], v172, vcc
	global_load_dwordx4 v[158:161], v173, vcc
